# 3456 layer-1 expert-weight transposes tiles moved from P0b into layer 0's in-proj phase (16 per block, on the 216 blocks without a third in-proj tile)
# speedup vs baseline: 1.0070x; 1.0060x over previous
; __device__ __forceinline__ TrJob tr_decode(const Params& p, char* ws, int job) {
;   TrJob t;
;   int l = job / TJ_PER_LAYER, rj = job % TJ_PER_LAYER;
;   if (rj < 640) {
;     t.src = p.w_in + (size_t)l * 1024 * 2560; t.K = 1024; t.N = 2560; t.kt = rj / 40; t.nt = rj % 40;
;     t.dst = (u16*)(ws + OFF_WINT) + (size_t)l * 2560 * 1024; t.mode = 0;
;   } else if (rj < 896) {
;     rj -= 640;
;     t.src = p.w_out + (size_t)l * 1024 * 1024; t.K = 1024; t.N = 1024; t.kt = rj / 16; t.nt = rj % 16;
;     t.dst = (u16*)(ws + OFF_WOUTT) + (size_t)l * 1024 * 1024; t.mode = 0;
;   } else {
;     rj -= 896;
;     int e = rj / 1536, q = rj % 1536;
;     size_t eo = (size_t)(l * 16 + e);
;     if (q < 512) {
;       t.src = p.w_gate + eo * 1024 * 2048; t.K = 1024; t.N = 2048; t.kt = q / 32; t.nt = q % 32;
;       t.dst = (u16*)(ws + OFF_WGUT) + eo * 4096 * 1024; t.mode = 1;
;     } else if (q < 1024) {
;       q -= 512;
;       t.src = p.w_up + eo * 1024 * 2048; t.K = 1024; t.N = 2048; t.kt = q / 32; t.nt = q % 32;
;       t.dst = (u16*)(ws + OFF_WGUT) + eo * 4096 * 1024; t.mode = 2;
;     } else {
;       q -= 1024;
;       t.src = p.w_down + eo * 2048 * 1024; t.K = 2048; t.N = 1024; t.kt = q / 16; t.nt = q % 16;
;       t.dst = (u16*)(ws + OFF_WDT) + eo * 1024 * 2048; t.mode = 0;
;     }
; __device__ __forceinline__ void p0_transposes(const Params& p, char* smem, int bid, int nb, int jlo, int jhi) {
;     ...
;   int j = jlo + bid * 2;
;   if (j < jhi) { tr_load(p, ws, j, tid, c0); tr_load(p, ws, j + 1, tid, c1); }
;   for (; j < jhi; j += 2 * nb) {
;     const int jn = j + 2 * nb;
;     if (jn < jhi) { tr_load(p, ws, jn, tid, n0); tr_load(p, ws, jn + 1, tid, n1); }
.LBB0_174:
	s_add_i32 s96, s97, s75
	s_cmp_gt_i32 s96, 0x917f
	s_cselect_b64 s[0:1], -1, 0
	s_and_b64 vcc, exec, s[0:1]
	s_cbranch_vccnz .LBB0_208
	s_mul_hi_i32 s10, s96, 0x5254e78f
	s_lshr_b32 s11, s10, 31
	s_ashr_i32 s10, s10, 13
	s_add_i32 s52, s10, s11
	s_mul_i32 s10, s52, 0xffff9c80
	s_add_i32 s10, s96, s10
	s_cmpk_gt_i32 s10, 0x27f
	s_mov_b64 s[58:59], -1
	s_cbranch_scc0 .LBB0_189
	s_cmpk_gt_u32 s10, 0x37f
	s_cbranch_scc0 .LBB0_186
	s_add_i32 s11, s10, 0xfc80
	s_and_b32 s33, s11, 0xffff
	s_mul_i32 s33, s33, 0xaaab
	s_lshr_b32 s33, s33, 26
	s_mul_i32 s40, s33, 0x600
	s_sub_i32 s11, s11, s40
	s_and_b32 s40, s11, 0xffff
	s_lshl_b32 s11, s52, 4
	s_add_i32 s54, s11, s33
	s_ashr_i32 s55, s54, 31
	s_lshl_b64 s[58:59], s[54:55], 23
	s_cmpk_gt_u32 s40, 0x1ff
	s_mov_b64 s[60:61], -1
	s_cbranch_scc0 .LBB0_183
	s_cmpk_gt_u32 s40, 0x3ff
	s_mov_b64 s[56:57], -1
	s_cbranch_scc0 .LBB0_180
	v_readlane_b32 s12, v238, 25
	s_add_i32 s11, s40, 0xfffffc00
	v_readlane_b32 s18, v238, 31
	v_readlane_b32 s19, v238, 32
	s_add_u32 s54, s18, s58
	v_readlane_b32 s13, v238, 26
	v_readlane_b32 s14, v238, 27
	v_readlane_b32 s15, v238, 28
	v_readlane_b32 s16, v238, 29
	v_readlane_b32 s17, v238, 30
	s_addc_u32 s55, s19, s59
	s_lshr_b32 s33, s11, 4
	s_and_b32 s11, s40, 15
	s_mov_b64 s[56:57], 0

; __device__ __forceinline__ TrJob tr_decode(const Params& p, char* ws, int job) {
;   TrJob t;
;   int l = job / TJ_PER_LAYER, rj = job % TJ_PER_LAYER;
;   if (rj < 640) {
;     t.src = p.w_in + (size_t)l * 1024 * 2560; t.K = 1024; t.N = 2560; t.kt = rj / 40; t.nt = rj % 40;
;     t.dst = (u16*)(ws + OFF_WINT) + (size_t)l * 2560 * 1024; t.mode = 0;
;   } else if (rj < 896) {
;     rj -= 640;
;     t.src = p.w_out + (size_t)l * 1024 * 1024; t.K = 1024; t.N = 1024; t.kt = rj / 16; t.nt = rj % 16;
;     t.dst = (u16*)(ws + OFF_WOUTT) + (size_t)l * 1024 * 1024; t.mode = 0;
;   } else {
;     rj -= 896;
;     int e = rj / 1536, q = rj % 1536;
;     size_t eo = (size_t)(l * 16 + e);
;     if (q < 512) {
;       t.src = p.w_gate + eo * 1024 * 2048; t.K = 1024; t.N = 2048; t.kt = q / 32; t.nt = q % 32;
;       t.dst = (u16*)(ws + OFF_WGUT) + eo * 4096 * 1024; t.mode = 1;
;     } else if (q < 1024) {
;       q -= 512;
;       t.src = p.w_up + eo * 1024 * 2048; t.K = 1024; t.N = 2048; t.kt = q / 32; t.nt = q % 32;
;       t.dst = (u16*)(ws + OFF_WGUT) + eo * 4096 * 1024; t.mode = 2;
;     } else {
;       q -= 1024;
;       t.src = p.w_down + eo * 2048 * 1024; t.K = 2048; t.N = 1024; t.kt = q / 16; t.nt = q % 16;
;       t.dst = (u16*)(ws + OFF_WDT) + eo * 1024 * 2048; t.mode = 0;
;     }
;   }
;   return t;
; }
; __device__ __forceinline__ void tr_load(const Params& p, char* ws, int job, int tid, float4 (&r)[4]) {
;   TrJob t = tr_decode(p, ws, job);
;   const int c4 = tid & 15, rr = tid >> 4;
;   const float* s0 = t.src + (size_t)(t.kt * 64 + rr) * t.N + t.nt * 64 + c4 * 4;
; #pragma unroll
;   for (int pp = 0; pp < 4; ++pp) {
;     f32x4 v_ = __builtin_nontemporal_load((const f32x4*)(s0 + (size_t)(16 * pp) * t.N));
;     r[pp] = make_float4(v_[0], v_[1], v_[2], v_[3]);
;   }
; }
.Ltrp1_check:
	v_readlane_b32 s0, v237, 29
	s_cmp_lg_u32 s0, 0
	s_cbranch_scc0 .LBB0_631
	v_readlane_b32 s0, v239, 0
	s_cmpk_lt_i32 s0, 296
	s_cbranch_scc1 .LBB0_631
	v_readlane_b32 s100, v236, 62
	v_readlane_b32 s101, v236, 63
	v_writelane_b32 v255, s64, 0
	v_writelane_b32 v255, s65, 1
	v_writelane_b32 v255, s66, 2
	v_writelane_b32 v255, s67, 3
	v_writelane_b32 v255, s68, 4
	v_writelane_b32 v255, s69, 5
	v_writelane_b32 v255, s70, 6
	v_writelane_b32 v255, s71, 7
	v_writelane_b32 v255, s72, 8
	v_writelane_b32 v255, s73, 9
	v_writelane_b32 v255, s74, 10
	v_writelane_b32 v255, s75, 11
	v_writelane_b32 v255, s76, 12
	v_writelane_b32 v255, s77, 13
	v_writelane_b32 v255, s78, 14
	v_writelane_b32 v255, s79, 15
	v_writelane_b32 v255, s80, 16
	v_writelane_b32 v255, s81, 17
	v_writelane_b32 v255, s82, 18
	v_writelane_b32 v255, s83, 19
	v_writelane_b32 v255, s84, 20
	v_writelane_b32 v255, s85, 21
	v_writelane_b32 v255, s86, 22
	v_writelane_b32 v255, s87, 23
	v_writelane_b32 v255, s88, 24
	v_writelane_b32 v255, s89, 25
	v_writelane_b32 v255, s90, 26
	v_writelane_b32 v255, s91, 27
	v_writelane_b32 v255, s92, 28
	v_writelane_b32 v255, s93, 29
	v_writelane_b32 v255, s94, 30
	v_writelane_b32 v255, s95, 31
	v_writelane_b32 v255, s96, 32
	v_writelane_b32 v255, s97, 33
	v_writelane_b32 v255, s98, 34
	v_writelane_b32 v255, s99, 35
	v_writelane_b32 v255, vcc_lo, 36
	v_writelane_b32 v255, vcc_hi, 37
	s_load_dwordx4 s[64:67], s[100:101], 0x40
	s_load_dwordx4 s[68:71], s[100:101], 0xc8
	s_load_dwordx2 s[72:73], s[100:101], 0xd8
	s_load_dwordx2 s[74:75], s[100:101], 0xe8
	v_and_b32_e32 v241, 15, v172
	v_lshrrev_b32_e32 v242, 4, v172
	v_lshlrev_b32_e32 v241, 4, v241
	v_mul_u32_u24_e32 v243, 0x104, v242
	v_add_u32_e32 v243, v243, v241
	v_and_b32_e32 v246, 7, v172
	v_lshrrev_b32_e32 v245, 3, v172
	v_mul_u32_u24_e32 v244, 0x820, v246
	v_lshl_add_u32 v244, v245, 2, v244
	v_lshlrev_b32_e32 v246, 4, v246
	v_readlane_b32 s76, v239, 0
	s_add_u32 s76, s76, 36952
	s_movk_i32 s77, 8
	s_mov_b32 s96, 0
	s_waitcnt lgkmcnt(0)
